# v031 plus 8 bytes of unreachable padding before the Fourier-2 setup (code placement of the later GEMM loops)
# speedup vs baseline: 1.0045x; 1.0045x over previous
.LBB0_713:
	s_andn2_b64 vcc, exec, s[76:77]
	s_waitcnt vmcnt(0) lgkmcnt(0)
	s_barrier
	s_cbranch_vccnz .LBB0_656
	ds_read2st64_b32 v[66:67], v64 offset1:1
	ds_read2st64_b32 v[76:77], v64 offset0:2 offset1:3
	ds_read2st64_b32 v[78:79], v64 offset0:4 offset1:5
	ds_read2st64_b32 v[80:81], v64 offset0:6 offset1:7
	ds_read2st64_b32 v[82:83], v64 offset0:8 offset1:9
	ds_read2st64_b32 v[84:85], v64 offset0:10 offset1:11
	ds_read2st64_b32 v[86:87], v64 offset0:12 offset1:13
	ds_read2st64_b32 v[88:89], v64 offset0:14 offset1:15
	ds_read2st64_b32 v[90:91], v64 offset0:16 offset1:17
	ds_read2st64_b32 v[116:117], v64 offset0:18 offset1:19
	ds_read2st64_b32 v[118:119], v64 offset0:20 offset1:21
	ds_read2st64_b32 v[120:121], v64 offset0:22 offset1:23
	ds_read2st64_b32 v[122:123], v64 offset0:24 offset1:25
	ds_read2st64_b32 v[124:125], v64 offset0:26 offset1:27
	ds_read2st64_b32 v[126:127], v64 offset0:28 offset1:29
	ds_read2st64_b32 v[128:129], v64 offset0:30 offset1:31
	ds_read2st64_b32 v[130:131], v64 offset0:32 offset1:33
	ds_read2st64_b32 v[132:133], v64 offset0:34 offset1:35
	ds_read2st64_b32 v[134:135], v64 offset0:36 offset1:37
	ds_read2st64_b32 v[136:137], v64 offset0:38 offset1:39
	ds_read2st64_b32 v[138:139], v64 offset0:40 offset1:41
	ds_read2st64_b32 v[140:141], v64 offset0:42 offset1:43
	ds_read2st64_b32 v[142:143], v64 offset0:44 offset1:45
	ds_read2st64_b32 v[148:149], v64 offset0:46 offset1:47
	ds_read2st64_b32 v[68:69], v64 offset0:58 offset1:59
	ds_read2st64_b32 v[150:151], v64 offset0:48 offset1:49
	ds_read2st64_b32 v[152:153], v64 offset0:50 offset1:51
	ds_read2st64_b32 v[154:155], v64 offset0:52 offset1:53
	ds_read2st64_b32 v[156:157], v64 offset0:54 offset1:55
	ds_read2st64_b32 v[72:73], v64 offset0:60 offset1:61
	ds_read2st64_b32 v[96:97], v64 offset0:62 offset1:63
	ds_read2st64_b32 v[162:163], v64 offset0:56 offset1:57
	s_waitcnt lgkmcnt(14)
	v_pk_fma_f32 v[98:99], v[50:51], v[74:75], v[76:77] op_sel_hi:[1,0,1] neg_lo:[0,0,1] neg_hi:[0,0,1]
	v_pk_fma_f32 v[104:105], v[48:49], v[74:75], v[66:67] op_sel_hi:[1,0,1] neg_lo:[0,0,1] neg_hi:[0,0,1]
	global_load_dwordx4 v[64:67], v146, s[30:31]
	global_load_dwordx4 v[48:51], v146, s[30:31] offset:32
	v_pk_mul_f32 v[164:165], v[104:105], v[104:105]
	s_waitcnt lgkmcnt(7)
	v_pk_fma_f32 v[70:71], v[26:27], v[74:75], v[68:69] op_sel_hi:[1,0,1] neg_lo:[0,0,1] neg_hi:[0,0,1]
	s_waitcnt lgkmcnt(2)
	v_pk_fma_f32 v[68:69], v[28:29], v[74:75], v[72:73] op_sel_hi:[1,0,1] neg_lo:[0,0,1] neg_hi:[0,0,1]
	s_waitcnt lgkmcnt(1)
	v_pk_fma_f32 v[72:73], v[30:31], v[74:75], v[96:97] op_sel_hi:[1,0,1] neg_lo:[0,0,1] neg_hi:[0,0,1]
	v_or_b32_e32 v26, s34, v161
	v_pk_mul_f32 v[160:161], v[98:99], v[98:99]
	v_pk_fma_f32 v[102:103], v[54:55], v[74:75], v[80:81] op_sel_hi:[1,0,1] neg_lo:[0,0,1] neg_hi:[0,0,1]
	v_pk_fma_f32 v[108:109], v[52:53], v[74:75], v[78:79] op_sel_hi:[1,0,1] neg_lo:[0,0,1] neg_hi:[0,0,1]
	v_pk_fma_f32 v[106:107], v[58:59], v[74:75], v[84:85] op_sel_hi:[1,0,1] neg_lo:[0,0,1] neg_hi:[0,0,1]
	v_pk_fma_f32 v[112:113], v[56:57], v[74:75], v[82:83] op_sel_hi:[1,0,1] neg_lo:[0,0,1] neg_hi:[0,0,1]
	v_pk_fma_f32 v[110:111], v[62:63], v[74:75], v[88:89] op_sel_hi:[1,0,1] neg_lo:[0,0,1] neg_hi:[0,0,1]
	v_pk_fma_f32 v[114:115], v[60:61], v[74:75], v[86:87] op_sel_hi:[1,0,1] neg_lo:[0,0,1] neg_hi:[0,0,1]
	v_pk_fma_f32 v[60:61], v[2:3], v[74:75], v[116:117] op_sel_hi:[1,0,1] neg_lo:[0,0,1] neg_hi:[0,0,1]
	v_pk_fma_f32 v[62:63], v[0:1], v[74:75], v[90:91] op_sel_hi:[1,0,1] neg_lo:[0,0,1] neg_hi:[0,0,1]
	v_pk_fma_f32 v[76:77], v[6:7], v[74:75], v[120:121] op_sel_hi:[1,0,1] neg_lo:[0,0,1] neg_hi:[0,0,1]
	v_pk_fma_f32 v[80:81], v[4:5], v[74:75], v[118:119] op_sel_hi:[1,0,1] neg_lo:[0,0,1] neg_hi:[0,0,1]
	v_pk_fma_f32 v[78:79], v[10:11], v[74:75], v[124:125] op_sel_hi:[1,0,1] neg_lo:[0,0,1] neg_hi:[0,0,1]
	v_pk_fma_f32 v[82:83], v[8:9], v[74:75], v[122:123] op_sel_hi:[1,0,1] neg_lo:[0,0,1] neg_hi:[0,0,1]
	v_pk_fma_f32 v[84:85], v[14:15], v[74:75], v[128:129] op_sel_hi:[1,0,1] neg_lo:[0,0,1] neg_hi:[0,0,1]
	v_pk_fma_f32 v[86:87], v[12:13], v[74:75], v[126:127] op_sel_hi:[1,0,1] neg_lo:[0,0,1] neg_hi:[0,0,1]
	v_pk_fma_f32 v[34:35], v[34:35], v[74:75], v[132:133] op_sel_hi:[1,0,1] neg_lo:[0,0,1] neg_hi:[0,0,1]
	v_pk_fma_f32 v[88:89], v[32:33], v[74:75], v[130:131] op_sel_hi:[1,0,1] neg_lo:[0,0,1] neg_hi:[0,0,1]
	v_pk_fma_f32 v[38:39], v[38:39], v[74:75], v[136:137] op_sel_hi:[1,0,1] neg_lo:[0,0,1] neg_hi:[0,0,1]
	v_pk_fma_f32 v[90:91], v[36:37], v[74:75], v[134:135] op_sel_hi:[1,0,1] neg_lo:[0,0,1] neg_hi:[0,0,1]
	v_pk_fma_f32 v[36:37], v[42:43], v[74:75], v[140:141] op_sel_hi:[1,0,1] neg_lo:[0,0,1] neg_hi:[0,0,1]
	v_pk_fma_f32 v[42:43], v[40:41], v[74:75], v[138:139] op_sel_hi:[1,0,1] neg_lo:[0,0,1] neg_hi:[0,0,1]
	v_pk_fma_f32 v[40:41], v[46:47], v[74:75], v[148:149] op_sel_hi:[1,0,1] neg_lo:[0,0,1] neg_hi:[0,0,1]
	v_pk_fma_f32 v[44:45], v[44:45], v[74:75], v[142:143] op_sel_hi:[1,0,1] neg_lo:[0,0,1] neg_hi:[0,0,1]
	v_pk_fma_f32 v[18:19], v[18:19], v[74:75], v[152:153] op_sel_hi:[1,0,1] neg_lo:[0,0,1] neg_hi:[0,0,1]
	v_pk_fma_f32 v[46:47], v[16:17], v[74:75], v[150:151] op_sel_hi:[1,0,1] neg_lo:[0,0,1] neg_hi:[0,0,1]
	v_pk_fma_f32 v[16:17], v[22:23], v[74:75], v[156:157] op_sel_hi:[1,0,1] neg_lo:[0,0,1] neg_hi:[0,0,1]
	v_pk_fma_f32 v[20:21], v[20:21], v[74:75], v[154:155] op_sel_hi:[1,0,1] neg_lo:[0,0,1] neg_hi:[0,0,1]
	s_waitcnt lgkmcnt(0)
	v_pk_fma_f32 v[22:23], v[24:25], v[74:75], v[162:163] op_sel_hi:[1,0,1] neg_lo:[0,0,1] neg_hi:[0,0,1]
	v_add_f32_e32 v74, v164, v165
	v_add_f32_e32 v74, v74, v160
	v_pk_mul_f32 v[168:169], v[108:109], v[108:109]
	v_add_f32_e32 v74, v74, v161
	v_add_f32_e32 v74, v74, v168
	v_pk_mul_f32 v[166:167], v[102:103], v[102:103]
	v_add_f32_e32 v74, v74, v169
	global_load_dwordx4 v[56:59], v146, s[30:31] offset:64
	global_load_dwordx4 v[52:55], v146, s[30:31] offset:96
	v_add_f32_e32 v74, v74, v166
	v_pk_mul_f32 v[172:173], v[112:113], v[112:113]
	v_add_f32_e32 v74, v74, v167
	v_add_f32_e32 v74, v74, v172
	v_pk_mul_f32 v[170:171], v[106:107], v[106:107]
	v_add_f32_e32 v74, v74, v173
	v_add_f32_e32 v74, v74, v170
	v_pk_mul_f32 v[178:179], v[114:115], v[114:115]
	v_add_f32_e32 v74, v74, v171
	v_add_f32_e32 v74, v74, v178
	v_pk_mul_f32 v[174:175], v[110:111], v[110:111]
	v_add_f32_e32 v74, v74, v179
	v_add_f32_e32 v74, v74, v174
	v_pk_mul_f32 v[180:181], v[62:63], v[62:63]
	v_add_f32_e32 v74, v74, v175
	v_add_f32_e32 v74, v74, v180
	v_pk_mul_f32 v[116:117], v[60:61], v[60:61]
	v_add_f32_e32 v74, v74, v181
	v_add_f32_e32 v74, v74, v116
	v_pk_mul_f32 v[118:119], v[80:81], v[80:81]
	v_add_f32_e32 v74, v74, v117
	v_add_f32_e32 v74, v74, v118
	v_pk_mul_f32 v[120:121], v[76:77], v[76:77]
	v_add_f32_e32 v74, v74, v119
	v_add_f32_e32 v74, v74, v120
	v_pk_mul_f32 v[122:123], v[82:83], v[82:83]
	v_add_f32_e32 v74, v74, v121
	v_add_f32_e32 v74, v74, v122
	v_pk_mul_f32 v[124:125], v[78:79], v[78:79]
	v_add_f32_e32 v74, v74, v123
	v_add_f32_e32 v74, v74, v124
	v_pk_mul_f32 v[126:127], v[86:87], v[86:87]
	v_add_f32_e32 v74, v74, v125
	v_add_f32_e32 v74, v74, v126
	v_pk_mul_f32 v[128:129], v[84:85], v[84:85]
	v_add_f32_e32 v74, v74, v127
	v_add_f32_e32 v74, v74, v128
	v_pk_mul_f32 v[130:131], v[88:89], v[88:89]
	v_add_f32_e32 v74, v74, v129
	v_add_f32_e32 v74, v74, v130
	v_pk_mul_f32 v[132:133], v[34:35], v[34:35]
	v_add_f32_e32 v74, v74, v131
	v_add_f32_e32 v74, v74, v132
	v_pk_mul_f32 v[134:135], v[90:91], v[90:91]
	v_add_f32_e32 v74, v74, v133
	v_add_f32_e32 v74, v74, v134
	v_pk_mul_f32 v[136:137], v[38:39], v[38:39]
	v_add_f32_e32 v74, v74, v135
	v_add_f32_e32 v74, v74, v136
	v_pk_mul_f32 v[138:139], v[42:43], v[42:43]
	v_add_f32_e32 v74, v74, v137
	v_add_f32_e32 v74, v74, v138
	v_pk_mul_f32 v[140:141], v[36:37], v[36:37]
	v_add_f32_e32 v74, v74, v139
	v_add_f32_e32 v74, v74, v140
	v_pk_mul_f32 v[142:143], v[44:45], v[44:45]
	v_add_f32_e32 v74, v74, v141
	v_add_f32_e32 v74, v74, v142
	v_pk_mul_f32 v[148:149], v[40:41], v[40:41]
	v_add_f32_e32 v74, v74, v143
	v_add_f32_e32 v74, v74, v148
	v_pk_mul_f32 v[150:151], v[46:47], v[46:47]
	v_add_f32_e32 v74, v74, v149
	v_add_f32_e32 v74, v74, v150
	v_pk_mul_f32 v[152:153], v[18:19], v[18:19]
	v_add_f32_e32 v74, v74, v151
	v_add_f32_e32 v74, v74, v152
	v_pk_mul_f32 v[154:155], v[20:21], v[20:21]
	v_add_f32_e32 v74, v74, v153
	v_add_f32_e32 v74, v74, v154
	v_pk_mul_f32 v[156:157], v[16:17], v[16:17]
	v_add_f32_e32 v74, v74, v155
	v_ashrrev_i32_e32 v27, 31, v26
	v_readlane_b32 s0, v255, 20
	v_add_f32_e32 v74, v74, v156
	v_lshlrev_b64 v[26:27], 12, v[26:27]
	v_readlane_b32 s1, v255, 21
	v_pk_mul_f32 v[24:25], v[22:23], v[22:23]
	v_add_f32_e32 v74, v74, v157
	v_lshl_add_u64 v[26:27], s[0:1], 0, v[26:27]
	v_add_f32_e32 v24, v74, v24
	v_pk_mul_f32 v[92:93], v[70:71], v[70:71]
	v_lshl_add_u64 v[100:101], v[26:27], 0, s[72:73]
	global_load_dwordx4 v[26:29], v146, s[30:31] offset:128
	global_load_dwordx4 v[0:3], v146, s[30:31] offset:160
	v_add_f32_e32 v24, v24, v25
	v_add_f32_e32 v24, v24, v92
	v_pk_mul_f32 v[94:95], v[68:69], v[68:69]
	v_add_f32_e32 v24, v24, v93
	v_add_f32_e32 v24, v24, v94
	v_pk_mul_f32 v[96:97], v[72:73], v[72:73]
	v_add_f32_e32 v24, v24, v95
	v_add_f32_e32 v24, v24, v96
	v_add_f32_e32 v74, v24, v97
	ds_bpermute_b32 v75, v75, v74
	global_load_dwordx4 v[8:11], v146, s[30:31] offset:192
	global_load_dwordx4 v[4:7], v146, s[30:31] offset:224
	global_load_dwordx4 v[30:33], v146, s[30:31] offset:256
	global_load_dwordx4 v[12:15], v146, s[30:31] offset:288
	global_load_dwordx4 v[92:95], v146, s[30:31] offset:320
	global_load_dwordx4 v[116:119], v146, s[30:31] offset:352
	v_lshlrev_b32_e32 v176, 3, v158
	s_waitcnt lgkmcnt(0)
	v_add_f32_e32 v74, v74, v75
	v_fmamk_f32 v74, v74, 0x3c000000, v213
	v_rsq_f32_e32 v74, v74
	v_lshl_add_u64 v[24:25], v[100:101], 0, v[176:177]
	global_load_dwordx4 v[120:123], v146, s[30:31] offset:384
	global_load_dwordx4 v[124:127], v146, s[30:31] offset:416
	global_load_dwordx4 v[128:131], v146, s[30:31] offset:448
	v_mul_f32_e32 v74, v145, v74
	v_pk_mul_f32 v[96:97], v[104:105], v[74:75] op_sel_hi:[1,0]
	s_waitcnt vmcnt(14)
	v_pk_mul_f32 v[64:65], v[64:65], v[96:97]
	v_pk_mul_f32 v[96:97], v[98:99], v[74:75] op_sel_hi:[1,0]
	v_cvt_pk_bf16_f32 v64, v64, v65
	v_pk_mul_f32 v[66:67], v[66:67], v[96:97]
	s_nop 0
	v_cvt_pk_bf16_f32 v65, v66, v67
	global_store_dwordx2 v[24:25], v[64:65], off
	v_pk_mul_f32 v[64:65], v[108:109], v[74:75] op_sel_hi:[1,0]
	s_waitcnt vmcnt(14)
	v_pk_mul_f32 v[48:49], v[48:49], v[64:65]
	v_pk_mul_f32 v[64:65], v[102:103], v[74:75] op_sel_hi:[1,0]
	v_cvt_pk_bf16_f32 v48, v48, v49
	v_pk_mul_f32 v[50:51], v[50:51], v[64:65]
	s_nop 0
	v_cvt_pk_bf16_f32 v49, v50, v51
	global_store_dwordx2 v[24:25], v[48:49], off offset:16
	v_pk_mul_f32 v[48:49], v[112:113], v[74:75] op_sel_hi:[1,0]
	v_pk_mul_f32 v[50:51], v[106:107], v[74:75] op_sel_hi:[1,0]
	s_waitcnt vmcnt(14)
	v_pk_mul_f32 v[48:49], v[56:57], v[48:49]
	v_pk_mul_f32 v[50:51], v[58:59], v[50:51]
	v_cvt_pk_bf16_f32 v48, v48, v49
	v_cvt_pk_bf16_f32 v49, v50, v51
	global_store_dwordx2 v[24:25], v[48:49], off offset:32
	v_pk_mul_f32 v[48:49], v[114:115], v[74:75] op_sel_hi:[1,0]
	s_waitcnt vmcnt(14)
	v_pk_mul_f32 v[48:49], v[52:53], v[48:49]
	s_nop 0
	v_cvt_pk_bf16_f32 v52, v48, v49
	v_pk_mul_f32 v[48:49], v[110:111], v[74:75] op_sel_hi:[1,0]
	s_nop 0
	v_pk_mul_f32 v[48:49], v[54:55], v[48:49]
	s_nop 0
	v_cvt_pk_bf16_f32 v53, v48, v49
	global_load_dwordx4 v[48:51], v146, s[30:31] offset:480
	s_nop 0
	global_store_dwordx2 v[24:25], v[52:53], off offset:48
	v_pk_mul_f32 v[52:53], v[62:63], v[74:75] op_sel_hi:[1,0]
	s_waitcnt vmcnt(15)
	v_pk_mul_f32 v[26:27], v[52:53], v[26:27]
	v_pk_mul_f32 v[52:53], v[60:61], v[74:75] op_sel_hi:[1,0]
	v_cvt_pk_bf16_f32 v26, v26, v27
	v_pk_mul_f32 v[28:29], v[52:53], v[28:29]
	s_nop 0
	v_cvt_pk_bf16_f32 v27, v28, v29
	global_store_dwordx2 v[24:25], v[26:27], off offset:64
	v_pk_mul_f32 v[26:27], v[80:81], v[74:75] op_sel_hi:[1,0]
	s_waitcnt vmcnt(15)
	v_pk_mul_f32 v[0:1], v[26:27], v[0:1]
	v_pk_mul_f32 v[26:27], v[76:77], v[74:75] op_sel_hi:[1,0]
	v_cvt_pk_bf16_f32 v0, v0, v1
	v_pk_mul_f32 v[2:3], v[26:27], v[2:3]
	s_nop 0
	v_cvt_pk_bf16_f32 v1, v2, v3
	global_store_dwordx2 v[24:25], v[0:1], off offset:80
	v_pk_mul_f32 v[0:1], v[82:83], v[74:75] op_sel_hi:[1,0]
	v_pk_mul_f32 v[2:3], v[78:79], v[74:75] op_sel_hi:[1,0]
	s_waitcnt vmcnt(15)
	v_pk_mul_f32 v[0:1], v[0:1], v[8:9]
	v_pk_mul_f32 v[2:3], v[2:3], v[10:11]
	v_cvt_pk_bf16_f32 v0, v0, v1
	v_cvt_pk_bf16_f32 v1, v2, v3
	global_store_dwordx2 v[24:25], v[0:1], off offset:96
	v_pk_mul_f32 v[0:1], v[86:87], v[74:75] op_sel_hi:[1,0]
	v_pk_mul_f32 v[2:3], v[84:85], v[74:75] op_sel_hi:[1,0]
	s_waitcnt vmcnt(15)
	v_pk_mul_f32 v[0:1], v[0:1], v[4:5]
	v_pk_mul_f32 v[2:3], v[2:3], v[6:7]
	v_cvt_pk_bf16_f32 v0, v0, v1
	v_cvt_pk_bf16_f32 v1, v2, v3
	global_store_dwordx2 v[24:25], v[0:1], off offset:112
	v_pk_mul_f32 v[0:1], v[88:89], v[74:75] op_sel_hi:[1,0]
	v_pk_mul_f32 v[2:3], v[34:35], v[74:75] op_sel_hi:[1,0]
	s_waitcnt vmcnt(15)
	v_pk_mul_f32 v[0:1], v[0:1], v[30:31]
	v_pk_mul_f32 v[2:3], v[2:3], v[32:33]
	v_cvt_pk_bf16_f32 v0, v0, v1
	v_cvt_pk_bf16_f32 v1, v2, v3
	global_store_dwordx2 v[24:25], v[0:1], off offset:128
	v_pk_mul_f32 v[0:1], v[90:91], v[74:75] op_sel_hi:[1,0]
	v_pk_mul_f32 v[2:3], v[38:39], v[74:75] op_sel_hi:[1,0]
	s_waitcnt vmcnt(15)
	v_pk_mul_f32 v[0:1], v[0:1], v[12:13]
	v_pk_mul_f32 v[2:3], v[2:3], v[14:15]
	v_cvt_pk_bf16_f32 v0, v0, v1
	v_cvt_pk_bf16_f32 v1, v2, v3
	global_store_dwordx2 v[24:25], v[0:1], off offset:144
	v_pk_mul_f32 v[0:1], v[42:43], v[74:75] op_sel_hi:[1,0]
	v_pk_mul_f32 v[2:3], v[36:37], v[74:75] op_sel_hi:[1,0]
	s_waitcnt vmcnt(15)
	v_pk_mul_f32 v[0:1], v[0:1], v[92:93]
	v_pk_mul_f32 v[2:3], v[2:3], v[94:95]
	v_cvt_pk_bf16_f32 v0, v0, v1
	v_cvt_pk_bf16_f32 v1, v2, v3
	global_store_dwordx2 v[24:25], v[0:1], off offset:160
	v_pk_mul_f32 v[0:1], v[44:45], v[74:75] op_sel_hi:[1,0]
	v_pk_mul_f32 v[2:3], v[40:41], v[74:75] op_sel_hi:[1,0]
	s_waitcnt vmcnt(15)
	v_pk_mul_f32 v[0:1], v[0:1], v[116:117]
	v_pk_mul_f32 v[2:3], v[2:3], v[118:119]
	v_cvt_pk_bf16_f32 v0, v0, v1
	v_cvt_pk_bf16_f32 v1, v2, v3
	global_store_dwordx2 v[24:25], v[0:1], off offset:176
	v_pk_mul_f32 v[0:1], v[46:47], v[74:75] op_sel_hi:[1,0]
	v_pk_mul_f32 v[2:3], v[18:19], v[74:75] op_sel_hi:[1,0]
	s_waitcnt vmcnt(15)
	v_pk_mul_f32 v[0:1], v[0:1], v[120:121]
	v_pk_mul_f32 v[2:3], v[2:3], v[122:123]
	v_cvt_pk_bf16_f32 v0, v0, v1
	v_cvt_pk_bf16_f32 v1, v2, v3
	global_store_dwordx2 v[24:25], v[0:1], off offset:192
	v_pk_mul_f32 v[0:1], v[20:21], v[74:75] op_sel_hi:[1,0]
	v_pk_mul_f32 v[2:3], v[16:17], v[74:75] op_sel_hi:[1,0]
	s_waitcnt vmcnt(15)
	v_pk_mul_f32 v[0:1], v[0:1], v[124:125]
	v_pk_mul_f32 v[2:3], v[2:3], v[126:127]
	v_cvt_pk_bf16_f32 v0, v0, v1
	v_cvt_pk_bf16_f32 v1, v2, v3
	global_store_dwordx2 v[24:25], v[0:1], off offset:208
	v_pk_mul_f32 v[0:1], v[22:23], v[74:75] op_sel_hi:[1,0]
	v_pk_mul_f32 v[2:3], v[70:71], v[74:75] op_sel_hi:[1,0]
	s_waitcnt vmcnt(15)
	v_pk_mul_f32 v[0:1], v[0:1], v[128:129]
	v_pk_mul_f32 v[2:3], v[2:3], v[130:131]
	v_cvt_pk_bf16_f32 v0, v0, v1
	v_cvt_pk_bf16_f32 v1, v2, v3
	global_store_dwordx2 v[24:25], v[0:1], off offset:224
	v_pk_mul_f32 v[0:1], v[68:69], v[74:75] op_sel_hi:[1,0]
	v_pk_mul_f32 v[2:3], v[72:73], v[74:75] op_sel_hi:[1,0]
	s_waitcnt vmcnt(12)
	v_pk_mul_f32 v[0:1], v[0:1], v[48:49]
	v_pk_mul_f32 v[2:3], v[2:3], v[50:51]
	v_cvt_pk_bf16_f32 v0, v0, v1
	v_cvt_pk_bf16_f32 v1, v2, v3
	global_store_dwordx2 v[24:25], v[0:1], off offset:240
	s_branch .LBB0_656
	s_nop 0
	s_nop 0
